# SB attn item epilogue: all gate/out_gain loads issued up front instead of 8 serialized load+drain rounds
# speedup vs baseline: 1.0375x; 1.0021x over previous
; __device__ __forceinline__ unsigned pk2(float lo, float hi) { f32x2 v = {lo, hi}; bf16x2_t b = __builtin_convertvector(v, bf16x2_t); return __builtin_bit_cast(unsigned, b); }
; __device__ __forceinline__ float bflo(unsigned u) { return __uint_as_float(u << 16); }
; __device__ __forceinline__ float bfhi(unsigned u) { return __uint_as_float(u & 0xffff0000u); }
; __device__ __forceinline__ float silu(float g) { return g * __builtin_amdgcn_rcpf(1.0f + __expf(-g)); }
; template <int MODE>
; __device__ __forceinline__ void attn_item(const AttnP& p, int b, int h, int qb, LAS unsigned char* lds) {
;     ...
;     float ss = 0.f;
; #pragma unroll
;     for (int d = 0; d < DV / 32; ++d)
; #pragma unroll
;         for (int i = 0; i < 16; ++i) {
;             float o = O[0][d][i] * inv0;
;             if (MODE == 0) o -= O[NC - 1][d][i] * inv1;
;             O[0][d][i] = o; ss += o * o;
;         }
;     ss += __shfl_xor(ss, 32);
;     float rn = 1.0f / sqrtf(ss * (1.0f / DV) + 1e-6f);
;     if (MODE == 0) rn *= p.oml;
;     int qrow_e = qrow; asm volatile("" : "+v"(qrow_e));
;     const size_t trow = (size_t)(tok0 + qrow_e);
; #pragma unroll
;     for (int d = 0; d < DV / 32; ++d)
; #pragma unroll
;         for (int g = 0; g < 4; ++g) {
;             const int dd = d * 32 + 8 * g + 4 * hh;
;             const u32x2 gr = *(const u32x2*)(P + trow * PP + gcol + dd);
;             const f32x4 og = *(const f32x4*)(p.out_gain + gaincol + dd);
;             const float o0 = O[0][d][4 * g] * rn * og[0] * silu(bflo(gr.x)), o1 = O[0][d][4 * g + 1] * rn * og[1] * silu(bfhi(gr.x));
;             const float o2 = O[0][d][4 * g + 2] * rn * og[2] * silu(bflo(gr.y)), o3 = O[0][d][4 * g + 3] * rn * og[3] * silu(bfhi(gr.y));
;             u32x2 wv; wv.x = pk2(o0, o1); wv.y = pk2(o2, o3);
;             *(u32x2*)(p.mixed + trow * 1024 + mixcol + dd) = wv;
.LBB0_490:
	v_mul_f32_e32 v0, v19, v19
	v_fmac_f32_e32 v0, v18, v18
	v_fmac_f32_e32 v0, v20, v20
	v_fmac_f32_e32 v0, v21, v21
	v_fmac_f32_e32 v0, v22, v22
	v_fmac_f32_e32 v0, v23, v23
	v_fmac_f32_e32 v0, v24, v24
	v_fmac_f32_e32 v0, v25, v25
	v_fmac_f32_e32 v0, v26, v26
	v_fmac_f32_e32 v0, v27, v27
	v_fmac_f32_e32 v0, v28, v28
	v_fmac_f32_e32 v0, v29, v29
	v_fmac_f32_e32 v0, v30, v30
	v_fmac_f32_e32 v0, v31, v31
	v_fmac_f32_e32 v0, v32, v32
	v_fmac_f32_e32 v0, v33, v33
	v_fmac_f32_e32 v0, v2, v2
	v_fmac_f32_e32 v0, v3, v3
	v_fmac_f32_e32 v0, v4, v4
	v_fmac_f32_e32 v0, v5, v5
	v_fmac_f32_e32 v0, v6, v6
	v_fmac_f32_e32 v0, v7, v7
	v_fmac_f32_e32 v0, v8, v8
	v_fmac_f32_e32 v0, v9, v9
	v_fmac_f32_e32 v0, v10, v10
	v_fmac_f32_e32 v0, v11, v11
	v_pk_mul_f32 v[38:39], v[12:13], v[12:13]
	v_pk_mul_f32 v[36:37], v[14:15], v[14:15]
	v_add_f32_e32 v0, v38, v0
	v_add_f32_e32 v0, v39, v0
	v_add_f32_e32 v0, v36, v0
	v_pk_mul_f32 v[34:35], v[16:17], v[16:17]
	v_add_f32_e32 v0, v37, v0
	v_add_f32_e32 v0, v34, v0
	v_add_f32_e32 v0, v35, v0
	ds_bpermute_b32 v34, v226, v0
	v_lshlrev_b32_e32 v39, 2, v87
	s_waitcnt lgkmcnt(0)
	v_add_f32_e32 v0, v0, v34
	v_fmamk_f32 v0, v0, 0x3c800000, v211
	v_cmp_gt_f32_e32 vcc, s74, v0
	v_mul_f32_e32 v34, 0x4f800000, v0
	s_nop 0
	v_cndmask_b32_e32 v0, v0, v34, vcc
	v_sqrt_f32_e32 v34, v0
	s_nop 0
	v_add_u32_e32 v35, -1, v34
	v_fma_f32 v36, -v35, v34, v0
	v_cmp_ge_f32_e64 s[0:1], 0, v36
	v_add_u32_e32 v36, 1, v34
	s_nop 0
	v_cndmask_b32_e64 v35, v34, v35, s[0:1]
	v_fma_f32 v34, -v36, v34, v0
	v_cmp_lt_f32_e64 s[0:1], 0, v34
	s_nop 1
	v_cndmask_b32_e64 v34, v35, v36, s[0:1]
	v_mul_f32_e32 v35, 0x37800000, v34
	v_cndmask_b32_e32 v34, v34, v35, vcc
	v_cmp_class_f32_e32 vcc, v0, v212
	s_nop 1
	v_cndmask_b32_e32 v0, v34, v0, vcc
	v_div_scale_f32 v34, s[0:1], v0, v0, 1.0
	v_rcp_f32_e32 v35, v34
	s_nop 0
	v_fma_f32 v36, -v34, v35, 1.0
	v_fmac_f32_e32 v35, v36, v35
	v_div_scale_f32 v36, vcc, 1.0, v0, 1.0
	v_mul_f32_e32 v37, v36, v35
	v_fma_f32 v38, -v34, v37, v36
	v_fmac_f32_e32 v37, v38, v35
	v_fma_f32 v34, -v34, v37, v36
	v_div_fmas_f32 v34, v34, v35, v37
	v_div_fixup_f32 v38, v34, v0, 1.0
	v_add_u32_e32 v34, s33, v86
	v_mov_b64_e32 v[36:37], s[46:47]
	v_mad_i64_i32 v[36:37], s[0:1], v34, s76, v[36:37]
	v_lshl_add_u64 v[36:37], v[36:37], 0, s[92:93]
	s_mov_b64 s[0:1], 0x1c00
	v_ashrrev_i32_e32 v35, 31, v34
	v_lshl_add_u64 v[40:41], v[36:37], 0, s[0:1]
	v_lshlrev_b32_e32 v0, 1, v87
	s_lshl_b32 s0, s20, 2
	v_lshlrev_b64 v[42:43], 11, v[34:35]
	v_lshl_add_u64 v[34:35], v[40:41], 0, v[0:1]
	s_add_u32 s0, s54, s0
	global_load_dwordx2 v[44:45], v[34:35], off
	global_load_dwordx2 v[122:123], v[34:35], off offset:16
	global_load_dwordx2 v[124:125], v[34:35], off offset:32
	global_load_dwordx2 v[126:127], v[34:35], off offset:48
	global_load_dwordx2 v[128:129], v[34:35], off offset:64
	global_load_dwordx2 v[130:131], v[34:35], off offset:80
	global_load_dwordx2 v[132:133], v[34:35], off offset:96
	global_load_dwordx2 v[134:135], v[34:35], off offset:112
	s_addc_u32 s1, s55, 0
	global_load_dwordx4 v[34:37], v39, s[0:1] offset:2048
	global_load_dwordx4 v[136:139], v39, s[0:1] offset:2080
	global_load_dwordx4 v[140:143], v39, s[0:1] offset:2112
	global_load_dwordx4 v[144:147], v39, s[0:1] offset:2144
	global_load_dwordx4 v[148:151], v39, s[0:1] offset:2176
	global_load_dwordx4 v[152:155], v39, s[0:1] offset:2208
	global_load_dwordx4 v[156:159], v39, s[0:1] offset:2240
	global_load_dwordx4 v[160:163], v39, s[0:1] offset:2272
	v_pk_mul_f32 v[18:19], v[18:19], v[38:39] op_sel_hi:[1,0]
	v_pk_mul_f32 v[20:21], v[20:21], v[38:39] op_sel_hi:[1,0]
	v_pk_mul_f32 v[22:23], v[22:23], v[38:39] op_sel_hi:[1,0]
	v_pk_mul_f32 v[24:25], v[24:25], v[38:39] op_sel_hi:[1,0]
	v_pk_mul_f32 v[26:27], v[26:27], v[38:39] op_sel_hi:[1,0]
	v_pk_mul_f32 v[28:29], v[28:29], v[38:39] op_sel_hi:[1,0]
	v_pk_mul_f32 v[30:31], v[30:31], v[38:39] op_sel_hi:[1,0]
	v_pk_mul_f32 v[2:3], v[2:3], v[38:39] op_sel_hi:[1,0]
	v_pk_mul_f32 v[4:5], v[4:5], v[38:39] op_sel_hi:[1,0]
	v_pk_mul_f32 v[6:7], v[6:7], v[38:39] op_sel_hi:[1,0]
	v_pk_mul_f32 v[8:9], v[8:9], v[38:39] op_sel_hi:[1,0]
	v_pk_mul_f32 v[10:11], v[10:11], v[38:39] op_sel_hi:[1,0]
	s_waitcnt vmcnt(0) lgkmcnt(0)
	v_lshlrev_b32_e32 v46, 16, v44
	v_and_b32_e32 v47, 0xffff0000, v44
	v_mul_f32_e32 v44, 0xbfb8aa3b, v46
	v_pk_mul_f32 v[18:19], v[34:35], v[18:19]
	v_mul_f32_e32 v34, 0xbfb8aa3b, v47
	v_exp_f32_e32 v44, v44
	v_exp_f32_e32 v34, v34
	v_pk_mul_f32 v[20:21], v[36:37], v[20:21]
	v_add_f32_e32 v44, 1.0, v44
	v_add_f32_e32 v34, 1.0, v34
	v_rcp_f32_e32 v48, v44
	v_rcp_f32_e32 v49, v34
	s_nop 0
	v_pk_mul_f32 v[34:35], v[48:49], v[46:47]
	s_nop 0
	v_pk_mul_f32 v[18:19], v[18:19], v[34:35]
	v_lshlrev_b32_e32 v34, 16, v45
	v_and_b32_e32 v35, 0xffff0000, v45
	v_mul_f32_e32 v44, 0xbfb8aa3b, v34
	v_mul_f32_e32 v36, 0xbfb8aa3b, v35
	v_exp_f32_e32 v44, v44
	v_exp_f32_e32 v36, v36
	v_add_f32_e32 v44, 1.0, v44
	v_add_f32_e32 v36, 1.0, v36
	v_rcp_f32_e32 v44, v44
	v_rcp_f32_e32 v45, v36
	s_nop 0
	v_pk_mul_f32 v[34:35], v[44:45], v[34:35]
	s_nop 0
	v_pk_mul_f32 v[20:21], v[20:21], v[34:35]
	v_cvt_pk_bf16_f32 v34, v18, v19
	v_lshl_add_u64 v[18:19], s[44:45], 0, v[42:43]
	v_lshl_add_u64 v[18:19], v[18:19], 0, s[92:93]
	v_cvt_pk_bf16_f32 v35, v20, v21
	v_lshl_add_u64 v[18:19], v[18:19], 0, v[0:1]
	v_or_b32_e32 v20, 16, v0
	v_mov_b32_e32 v21, v1
	global_store_dwordx2 v[18:19], v[34:35], off offset:1024
	v_lshl_add_u64 v[20:21], v[40:41], 0, v[20:21]
	v_mov_b64_e32 v[20:21], v[122:123]
	s_nop 0
	v_mov_b64_e32 v[34:35], v[136:137]
	v_mov_b64_e32 v[36:37], v[138:139]
	v_lshlrev_b32_e32 v42, 16, v20
	v_and_b32_e32 v43, 0xffff0000, v20
; __device__ __forceinline__ unsigned pk2(float lo, float hi) { f32x2 v = {lo, hi}; bf16x2_t b = __builtin_convertvector(v, bf16x2_t); return __builtin_bit_cast(unsigned, b); }
; __device__ __forceinline__ float bflo(unsigned u) { return __uint_as_float(u << 16); }
; __device__ __forceinline__ float bfhi(unsigned u) { return __uint_as_float(u & 0xffff0000u); }
; __device__ __forceinline__ float silu(float g) { return g * __builtin_amdgcn_rcpf(1.0f + __expf(-g)); }
; template <int MODE>
; __device__ __forceinline__ void attn_item(const AttnP& p, int b, int h, int qb, LAS unsigned char* lds) {
;     ...
; #pragma unroll
;     for (int d = 0; d < DV / 32; ++d)
; #pragma unroll
;         for (int g = 0; g < 4; ++g) {
;             const int dd = d * 32 + 8 * g + 4 * hh;
;             const u32x2 gr = *(const u32x2*)(P + trow * PP + gcol + dd);
;             const f32x4 og = *(const f32x4*)(p.out_gain + gaincol + dd);
;             const float o0 = O[0][d][4 * g] * rn * og[0] * silu(bflo(gr.x)), o1 = O[0][d][4 * g + 1] * rn * og[1] * silu(bfhi(gr.x));
;             const float o2 = O[0][d][4 * g + 2] * rn * og[2] * silu(bflo(gr.y)), o3 = O[0][d][4 * g + 3] * rn * og[3] * silu(bfhi(gr.y));
;             u32x2 wv; wv.x = pk2(o0, o1); wv.y = pk2(o2, o3);
;             *(u32x2*)(p.mixed + trow * 1024 + mixcol + dd) = wv;
	v_mul_f32_e32 v20, 0xbfb8aa3b, v42
	v_exp_f32_e32 v20, v20
	v_pk_mul_f32 v[22:23], v[34:35], v[22:23]
	v_pk_mul_f32 v[24:25], v[36:37], v[24:25]
	v_add_f32_e32 v20, 1.0, v20
	v_rcp_f32_e32 v44, v20
	v_mul_f32_e32 v20, 0xbfb8aa3b, v43
	v_exp_f32_e32 v20, v20
	s_nop 0
	v_add_f32_e32 v20, 1.0, v20
	v_rcp_f32_e32 v45, v20
	v_lshlrev_b32_e32 v20, 16, v21
	v_and_b32_e32 v21, 0xffff0000, v21
	v_pk_mul_f32 v[34:35], v[44:45], v[42:43]
	s_nop 0
	v_pk_mul_f32 v[22:23], v[22:23], v[34:35]
	v_mul_f32_e32 v34, 0xbfb8aa3b, v20
	v_mul_f32_e32 v35, 0xbfb8aa3b, v21
	v_exp_f32_e32 v34, v34
	v_exp_f32_e32 v35, v35
	v_cvt_pk_bf16_f32 v22, v22, v23
	v_add_f32_e32 v34, 1.0, v34
	v_add_f32_e32 v35, 1.0, v35
	v_rcp_f32_e32 v34, v34
	v_rcp_f32_e32 v35, v35
	s_nop 0
	v_pk_mul_f32 v[20:21], v[34:35], v[20:21]
	s_nop 0
	v_pk_mul_f32 v[20:21], v[24:25], v[20:21]
	s_nop 0
	v_cvt_pk_bf16_f32 v23, v20, v21
	v_or_b32_e32 v20, 32, v0
	v_mov_b32_e32 v21, v1
	global_store_dwordx2 v[18:19], v[22:23], off offset:1040
	v_lshl_add_u64 v[20:21], v[40:41], 0, v[20:21]
	v_mov_b64_e32 v[24:25], v[124:125]
	s_nop 0
	v_mov_b64_e32 v[20:21], v[140:141]
	v_mov_b64_e32 v[22:23], v[142:143]
	v_lshlrev_b32_e32 v34, 16, v24
	v_and_b32_e32 v35, 0xffff0000, v24
	v_mul_f32_e32 v24, 0xbfb8aa3b, v34
	v_exp_f32_e32 v24, v24
	v_pk_mul_f32 v[20:21], v[26:27], v[20:21]
	v_pk_mul_f32 v[22:23], v[28:29], v[22:23]
	v_add_f32_e32 v24, 1.0, v24
	v_rcp_f32_e32 v36, v24
	v_mul_f32_e32 v24, 0xbfb8aa3b, v35
	v_exp_f32_e32 v24, v24
	s_nop 0
	v_add_f32_e32 v24, 1.0, v24
	v_rcp_f32_e32 v37, v24
	v_lshlrev_b32_e32 v24, 16, v25
	v_and_b32_e32 v25, 0xffff0000, v25
	v_pk_mul_f32 v[26:27], v[36:37], v[34:35]
	s_nop 0
	v_pk_mul_f32 v[20:21], v[20:21], v[26:27]
	v_mul_f32_e32 v26, 0xbfb8aa3b, v24
	v_mul_f32_e32 v27, 0xbfb8aa3b, v25
	v_exp_f32_e32 v26, v26
	v_exp_f32_e32 v27, v27
	v_cvt_pk_bf16_f32 v20, v20, v21
	v_add_f32_e32 v26, 1.0, v26
	v_add_f32_e32 v27, 1.0, v27
	v_rcp_f32_e32 v26, v26
	v_rcp_f32_e32 v27, v27
	s_nop 0
	v_pk_mul_f32 v[24:25], v[26:27], v[24:25]
	s_nop 0
	v_pk_mul_f32 v[22:23], v[22:23], v[24:25]
	s_nop 0
	v_cvt_pk_bf16_f32 v21, v22, v23
	global_store_dwordx2 v[18:19], v[20:21], off offset:1056
	v_or_b32_e32 v20, 48, v0
	v_mov_b32_e32 v21, v1
	v_lshl_add_u64 v[20:21], v[40:41], 0, v[20:21]
	v_mov_b64_e32 v[24:25], v[126:127]
	s_nop 0
	v_mov_b64_e32 v[20:21], v[144:145]
	v_mov_b64_e32 v[22:23], v[146:147]
	v_lshlrev_b32_e32 v26, 16, v24
	v_and_b32_e32 v27, 0xffff0000, v24
	v_mul_f32_e32 v24, 0xbfb8aa3b, v26
	v_exp_f32_e32 v24, v24
	v_pk_mul_f32 v[20:21], v[30:31], v[20:21]
	v_add_f32_e32 v24, 1.0, v24
	v_rcp_f32_e32 v28, v24
	v_mul_f32_e32 v24, 0xbfb8aa3b, v27
	v_exp_f32_e32 v24, v24
	s_nop 0
	v_add_f32_e32 v24, 1.0, v24
	v_rcp_f32_e32 v29, v24
	v_lshlrev_b32_e32 v24, 16, v25
	v_and_b32_e32 v25, 0xffff0000, v25
	v_pk_mul_f32 v[26:27], v[28:29], v[26:27]
	s_nop 0
	v_pk_mul_f32 v[20:21], v[20:21], v[26:27]
	v_mul_f32_e32 v26, 0xbfb8aa3b, v24
	v_mul_f32_e32 v27, 0xbfb8aa3b, v25
	v_exp_f32_e32 v26, v26
	v_exp_f32_e32 v27, v27
	v_pk_mul_f32 v[28:29], v[32:33], v[38:39] op_sel_hi:[1,0]
	v_cvt_pk_bf16_f32 v20, v20, v21
	v_add_f32_e32 v26, 1.0, v26
	v_add_f32_e32 v27, 1.0, v27
	v_rcp_f32_e32 v26, v26
	v_rcp_f32_e32 v27, v27
	v_pk_mul_f32 v[22:23], v[28:29], v[22:23]
	v_pk_mul_f32 v[24:25], v[26:27], v[24:25]
	s_nop 0
	v_pk_mul_f32 v[22:23], v[22:23], v[24:25]
	s_nop 0
	v_cvt_pk_bf16_f32 v21, v22, v23
	global_store_dwordx2 v[18:19], v[20:21], off offset:1072
	v_or_b32_e32 v20, 64, v0
	v_mov_b32_e32 v21, v1
	v_lshl_add_u64 v[20:21], v[40:41], 0, v[20:21]
	v_mov_b64_e32 v[20:21], v[128:129]
	s_nop 0
	v_mov_b64_e32 v[22:23], v[148:149]
	v_mov_b64_e32 v[24:25], v[150:151]
	v_lshlrev_b32_e32 v26, 16, v20
	v_and_b32_e32 v27, 0xffff0000, v20
	v_mul_f32_e32 v20, 0xbfb8aa3b, v26
	v_exp_f32_e32 v20, v20
	v_pk_mul_f32 v[2:3], v[2:3], v[22:23]
	v_pk_mul_f32 v[4:5], v[4:5], v[24:25]
	v_add_f32_e32 v20, 1.0, v20
	v_rcp_f32_e32 v28, v20
	v_mul_f32_e32 v20, 0xbfb8aa3b, v27
	v_exp_f32_e32 v20, v20
	s_nop 0
	v_add_f32_e32 v20, 1.0, v20
	v_rcp_f32_e32 v29, v20
	v_lshlrev_b32_e32 v20, 16, v21
	v_and_b32_e32 v21, 0xffff0000, v21
; __device__ __forceinline__ unsigned pk2(float lo, float hi) { f32x2 v = {lo, hi}; bf16x2_t b = __builtin_convertvector(v, bf16x2_t); return __builtin_bit_cast(unsigned, b); }
; __device__ __forceinline__ float bflo(unsigned u) { return __uint_as_float(u << 16); }
; __device__ __forceinline__ float bfhi(unsigned u) { return __uint_as_float(u & 0xffff0000u); }
; __device__ __forceinline__ float silu(float g) { return g * __builtin_amdgcn_rcpf(1.0f + __expf(-g)); }
; template <int MODE>
; __device__ __forceinline__ void attn_item(const AttnP& p, int b, int h, int qb, LAS unsigned char* lds) {
;     ...
; #pragma unroll
;     for (int d = 0; d < DV / 32; ++d)
; #pragma unroll
;         for (int g = 0; g < 4; ++g) {
;             const int dd = d * 32 + 8 * g + 4 * hh;
;             const u32x2 gr = *(const u32x2*)(P + trow * PP + gcol + dd);
;             const f32x4 og = *(const f32x4*)(p.out_gain + gaincol + dd);
;             const float o0 = O[0][d][4 * g] * rn * og[0] * silu(bflo(gr.x)), o1 = O[0][d][4 * g + 1] * rn * og[1] * silu(bfhi(gr.x));
;             const float o2 = O[0][d][4 * g + 2] * rn * og[2] * silu(bflo(gr.y)), o3 = O[0][d][4 * g + 3] * rn * og[3] * silu(bfhi(gr.y));
;             u32x2 wv; wv.x = pk2(o0, o1); wv.y = pk2(o2, o3);
;             *(u32x2*)(p.mixed + trow * 1024 + mixcol + dd) = wv;
	v_pk_mul_f32 v[22:23], v[28:29], v[26:27]
	s_nop 0
	v_pk_mul_f32 v[2:3], v[2:3], v[22:23]
	v_mul_f32_e32 v22, 0xbfb8aa3b, v20
	v_mul_f32_e32 v23, 0xbfb8aa3b, v21
	v_exp_f32_e32 v22, v22
	v_exp_f32_e32 v23, v23
	v_cvt_pk_bf16_f32 v2, v2, v3
	v_add_f32_e32 v22, 1.0, v22
	v_add_f32_e32 v23, 1.0, v23
	v_rcp_f32_e32 v22, v22
	v_rcp_f32_e32 v23, v23
	s_nop 0
	v_pk_mul_f32 v[20:21], v[22:23], v[20:21]
	s_nop 0
	v_pk_mul_f32 v[4:5], v[4:5], v[20:21]
	s_nop 0
	v_cvt_pk_bf16_f32 v3, v4, v5
	global_store_dwordx2 v[18:19], v[2:3], off offset:1088
	v_or_b32_e32 v2, 0x50, v0
	v_mov_b32_e32 v3, v1
	v_lshl_add_u64 v[2:3], v[40:41], 0, v[2:3]
	v_mov_b64_e32 v[20:21], v[130:131]
	s_nop 0
	v_mov_b64_e32 v[2:3], v[152:153]
	v_mov_b64_e32 v[4:5], v[154:155]
	v_lshlrev_b32_e32 v22, 16, v20
	v_and_b32_e32 v23, 0xffff0000, v20
	v_mul_f32_e32 v20, 0xbfb8aa3b, v22
	v_pk_mul_f32 v[2:3], v[6:7], v[2:3]
	v_mul_f32_e32 v6, 0xbfb8aa3b, v23
	v_exp_f32_e32 v20, v20
	v_exp_f32_e32 v6, v6
	v_pk_mul_f32 v[4:5], v[8:9], v[4:5]
	v_add_f32_e32 v20, 1.0, v20
	v_add_f32_e32 v6, 1.0, v6
	v_rcp_f32_e32 v24, v20
	v_rcp_f32_e32 v25, v6
	s_nop 0
	v_pk_mul_f32 v[6:7], v[24:25], v[22:23]
	s_nop 0
	v_pk_mul_f32 v[2:3], v[2:3], v[6:7]
	v_lshlrev_b32_e32 v6, 16, v21
	v_and_b32_e32 v7, 0xffff0000, v21
	v_mul_f32_e32 v20, 0xbfb8aa3b, v6
	v_mul_f32_e32 v8, 0xbfb8aa3b, v7
	v_exp_f32_e32 v20, v20
	v_exp_f32_e32 v8, v8
	v_cvt_pk_bf16_f32 v2, v2, v3
	v_add_f32_e32 v20, 1.0, v20
	v_add_f32_e32 v8, 1.0, v8
	v_rcp_f32_e32 v20, v20
	v_rcp_f32_e32 v21, v8
	s_nop 0
	v_pk_mul_f32 v[6:7], v[20:21], v[6:7]
	s_nop 0
	v_pk_mul_f32 v[4:5], v[4:5], v[6:7]
	s_nop 0
	v_cvt_pk_bf16_f32 v3, v4, v5
	global_store_dwordx2 v[18:19], v[2:3], off offset:1104
	v_or_b32_e32 v2, 0x60, v0
	v_mov_b32_e32 v3, v1
	v_lshl_add_u64 v[2:3], v[40:41], 0, v[2:3]
	v_mov_b64_e32 v[6:7], v[132:133]
	s_nop 0
	v_mov_b64_e32 v[2:3], v[156:157]
	v_mov_b64_e32 v[4:5], v[158:159]
	v_or_b32_e32 v0, 0x70, v0
	v_lshlrev_b32_e32 v8, 16, v6
	v_and_b32_e32 v9, 0xffff0000, v6
	v_mul_f32_e32 v6, 0xbfb8aa3b, v8
	v_exp_f32_e32 v6, v6
	v_pk_mul_f32 v[2:3], v[10:11], v[2:3]
	v_pk_mul_f32 v[10:11], v[12:13], v[38:39] op_sel_hi:[1,0]
	v_pk_mul_f32 v[12:13], v[14:15], v[38:39] op_sel_hi:[1,0]
	v_add_f32_e32 v6, 1.0, v6
	v_rcp_f32_e32 v20, v6
	v_mul_f32_e32 v6, 0xbfb8aa3b, v9
	v_exp_f32_e32 v6, v6
	v_pk_mul_f32 v[4:5], v[10:11], v[4:5]
	v_add_f32_e32 v6, 1.0, v6
	v_rcp_f32_e32 v21, v6
	v_lshlrev_b32_e32 v6, 16, v7
	v_and_b32_e32 v7, 0xffff0000, v7
	v_pk_mul_f32 v[8:9], v[20:21], v[8:9]
	s_nop 0
	v_pk_mul_f32 v[2:3], v[2:3], v[8:9]
	v_mul_f32_e32 v8, 0xbfb8aa3b, v6
	v_mul_f32_e32 v9, 0xbfb8aa3b, v7
	v_exp_f32_e32 v8, v8
	v_exp_f32_e32 v9, v9
	v_cvt_pk_bf16_f32 v2, v2, v3
	v_add_f32_e32 v8, 1.0, v8
	v_add_f32_e32 v9, 1.0, v9
	v_rcp_f32_e32 v8, v8
	v_rcp_f32_e32 v9, v9
	s_nop 0
	v_pk_mul_f32 v[6:7], v[8:9], v[6:7]
	s_nop 0
	v_pk_mul_f32 v[4:5], v[4:5], v[6:7]
	s_nop 0
	v_cvt_pk_bf16_f32 v3, v4, v5
	global_store_dwordx2 v[18:19], v[2:3], off offset:1120
	v_lshl_add_u64 v[2:3], v[40:41], 0, v[0:1]
	v_mov_b64_e32 v[2:3], v[134:135]
	s_nop 0
	v_mov_b64_e32 v[4:5], v[160:161]
	v_mov_b64_e32 v[6:7], v[162:163]
	s_mov_b64 s[0:1], 0
	v_lshlrev_b32_e32 v8, 16, v2
	v_mul_f32_e32 v0, 0xbfb8aa3b, v8
	v_exp_f32_e32 v0, v0
	v_and_b32_e32 v9, 0xffff0000, v2
	v_lshlrev_b32_e32 v2, 16, v3
	v_pk_mul_f32 v[4:5], v[12:13], v[4:5]
	v_add_f32_e32 v0, 1.0, v0
	v_rcp_f32_e32 v10, v0
	v_mul_f32_e32 v0, 0xbfb8aa3b, v9
	v_exp_f32_e32 v0, v0
	v_and_b32_e32 v3, 0xffff0000, v3
	v_add_f32_e32 v0, 1.0, v0
	v_rcp_f32_e32 v11, v0
	v_mul_f32_e32 v0, 0xbfb8aa3b, v2
	v_exp_f32_e32 v0, v0
	v_pk_mul_f32 v[8:9], v[10:11], v[8:9]
	s_nop 0
	v_pk_mul_f32 v[4:5], v[4:5], v[8:9]
	v_add_f32_e32 v0, 1.0, v0
	v_rcp_f32_e32 v8, v0
	v_mul_f32_e32 v0, 0xbfb8aa3b, v3
	v_exp_f32_e32 v0, v0
	v_pk_mul_f32 v[10:11], v[16:17], v[38:39] op_sel_hi:[1,0]
	v_cvt_pk_bf16_f32 v4, v4, v5
	v_pk_mul_f32 v[6:7], v[10:11], v[6:7]
	v_add_f32_e32 v0, 1.0, v0
	v_rcp_f32_e32 v9, v0
	s_nop 0
	v_pk_mul_f32 v[2:3], v[8:9], v[2:3]
	s_nop 0
	v_pk_mul_f32 v[2:3], v[6:7], v[2:3]
	s_nop 0
	v_cvt_pk_bf16_f32 v5, v2, v3
	global_store_dwordx2 v[18:19], v[4:5], off offset:1136
